# strategy 7.4: in-proj K-loop per-cluster s_setprio flips removed, static prio 1 for the wr=1 half during the phase
# baseline (speedup 1.0000x reference)
; #define GAS __attribute__((address_space(1)))
;     __device__ __forceinline__ GAS float* outp() const { return (GAS float*)rd(17); }
;     __device__ __forceinline__ GAS unsigned char* wsp() const { return (GAS unsigned char*)rd(18); }
; #define F_qng F.in(9)
; __global__ void __launch_bounds__(512, 2) mega_fwd(Params p) {
;     ...
;         if (IN(pb + 1)) { pg8::Gemm g{(const GAS bf16*)(F.wsp() + WS_XN), (const GAS bf16*)(F.wsp() + WS_WIN) + (size_t)l * NPROJ * D, 0, 0, MTOT / 256, NPROJ / 256, 1, D, 0, WGM_PROJ};
;             pg8::Order S; S.init(g, F.G, (int)blockIdx.x);
;             pg8::EpiProj E{l, F.wsp(), F.outp(), F_qng + l * 128, F_kng + l * 128, (const GAS float*)(F.wsp() + WS_LB) + l * 1024};
;             pg8::gemm_phase(F.lds, g, S, E, F.wave);
.LBB0_172:
	v_readlane_b32 s98, v243, 62
	s_nop 0
	s_cmp_eq_u32 s98, 0
	s_cbranch_scc0 .Lprio_skip
	s_setprio 1

; #define GAS __attribute__((address_space(1)))
; #define PG8_STAGE(bufoff, gbase, voff) do { _Pragma("unroll") for (int _i = 0; _i < 2; ++_i) \
;         __builtin_amdgcn_global_load_lds((const GAS unsigned*)((const GAS char*)(gbase) + (voff)[_i]), (LAS unsigned*)(lds + (bufoff) + ldsw + _i * 8192), 16, 0, 0); } while (0)
; #define PG8_LDA(dst, b, h) do { _Pragma("unroll") for (int m = 0; m < 4; ++m) _Pragma("unroll") for (int k = 0; k < 2; ++k) dst[m][k] = *(const LAS bf16x8*)(lds + PG8_SA(b, h) + aoff + m * 2048 + k * 1024); } while (0)
; #define PG8_LDB(dst, b, h) do { _Pragma("unroll") for (int n = 0; n < 2; ++n) _Pragma("unroll") for (int k = 0; k < 2; ++k) dst[n][k] = *(const LAS bf16x8*)(lds + PG8_SB(b, h) + boff + n * 2048 + k * 1024); } while (0)
; #define PG8_WAIT_V(n) asm volatile("s_waitcnt vmcnt(" #n ")" ::: "memory")
; #define PG8_WAIT_L(n) asm volatile("s_waitcnt lgkmcnt(" #n ")" ::: "memory")
; #define PG8_BAR __builtin_amdgcn_s_barrier()
; #define PG8_SCHED __builtin_amdgcn_sched_barrier(0)
;     ...
;         const bool has_next = S.template next<MODE>(ui + 1, nxt);
;         const GAS char* nA = has_next ? (const GAS char*)(g.A + (size_t)nxt.seg * g.a_seg) + (size_t)nxt.pm * tstep + (MODE ? (size_t)nxt.k0 * kstep : 0) : cA; const GAS char* nB = has_next ? (const GAS char*)(g.Bt + (size_t)nxt.seg * g.b_seg) + (size_t)nxt.pn * tstep + (MODE ? (size_t)nxt.k0 * kstep : 0) : cB;
;         const int nt = MODE == 0 ? K / BK : cur.nk;
;         for (int t = 0; t < nt; t += 2) {
;             const bool last = (t == nt - 2);
;             const GAS char* a1 = cA + (size_t)(t + 1) * kstep;
;             const GAS char* a2 = last ? nA : cA + (size_t)(t + 2) * kstep; const GAS char* b2 = last ? nB : cB + (size_t)(t + 2) * kstep;
;             const GAS char* a3 = a2 + kstep; const GAS char* b3 = b2 + kstep;
;             PG8_LDB(B0, 0, 0); PG8_LDB(B1, 0, 1); PG8_SCHED; PG8_LDA(At, 0, 0); PG8_STAGE(PG8_SA(1, 1), a1 + hstep, voffA);
;             PG8_WAIT_V(8); PG8_WAIT_L(0); PG8_BAR; PG8_MMA(0, 0, At, B0); PG8_MMA(0, 1, At, B1); PG8_BAR; PG8_SCHED;
;             PG8_LDA(At, 0, 1); PG8_STAGE(PG8_SB(0, 0), b2, voffB); PG8_STAGE(PG8_SB(0, 1), b2 + hstep, voffB); PG8_STAGE(PG8_SA(0, 0), a2, voffA);
;             PG8_WAIT_V(8); PG8_WAIT_L(0); PG8_BAR; PG8_MMA(1, 0, At, B0); PG8_MMA(1, 1, At, B1); PG8_BAR; PG8_SCHED;
.LBB0_189:
	s_ashr_i32 s89, s88, 31
	s_lshl_b64 s[8:9], s[88:89], 19
	s_add_u32 s8, s13, s8
	s_addc_u32 s9, s14, s9
	s_and_b64 s[26:27], s[60:61], exec
	s_cselect_b32 s17, s9, s37
	s_cselect_b32 s20, s8, s36
	s_ashr_i32 s93, s92, 31
	s_lshl_b64 s[26:27], s[92:93], 19
	s_add_u32 s26, s15, s26
	s_addc_u32 s27, s68, s27
	s_and_b64 s[52:53], s[60:61], exec
	s_cselect_b32 s25, s27, s35
	s_cselect_b32 s62, s26, s34
	s_add_u32 s63, s34, 0x100
	s_addc_u32 s64, s35, 0
	s_add_u32 s34, s36, 0x40080
	s_addc_u32 s35, s37, 0
	s_mov_b32 s65, -2
	s_add_u32 s36, s34, 0xfffc0080
	s_addc_u32 s37, s35, -1
	s_add_i32 s75, 0, 0x10000
	s_cmp_eq_u32 s65, 12
	s_cselect_b32 s53, s17, s37
	s_cselect_b32 s52, s20, s36
	s_cselect_b32 s37, s25, s64
	s_cselect_b32 s36, s62, s63
	s_add_i32 s89, 0, 0x14000
	v_add_u32_e32 v156, s75, v218
	v_add_u32_e32 v172, s89, v218
	ds_read_b128 v[128:131], v156
	ds_read_b128 v[132:135], v156 offset:1024
	ds_read_b128 v[152:155], v156 offset:2048
	ds_read_b128 v[156:159], v156 offset:3072
	ds_read_b128 v[160:163], v172
	ds_read_b128 v[164:167], v172 offset:1024
	ds_read_b128 v[168:171], v172 offset:2048
	ds_read_b128 v[182:185], v172 offset:3072
	v_lshl_add_u64 v[230:231], s[34:35], 0, v[150:151]
	s_add_i32 m0, s56, 0xc000
	ds_read_b128 v[186:189], v220
	ds_read_b128 v[190:193], v220 offset:1024
	ds_read_b128 v[194:197], v220 offset:2048
	ds_read_b128 v[198:201], v220 offset:3072
	ds_read_b128 v[202:205], v220 offset:4096
	ds_read_b128 v[206:209], v220 offset:5120
	ds_read_b128 v[222:225], v220 offset:6144
	ds_read_b128 v[226:229], v220 offset:7168
	global_load_lds_dwordx4 v[230:231], off
	v_lshl_add_u64 v[230:231], s[34:35], 0, v[148:149]
	s_add_i32 m0, s56, 0xe000
	s_nop 0
	global_load_lds_dwordx4 v[230:231], off
	s_waitcnt vmcnt(8)
	s_waitcnt lgkmcnt(0)
	s_barrier
	s_waitcnt lgkmcnt(0)
	v_mfma_f32_16x16x32_bf16 v[124:127], v[128:131], v[186:189], 0
	v_mfma_f32_16x16x32_bf16 v[120:123], v[152:155], v[186:189], 0
	v_mfma_f32_16x16x32_bf16 v[108:111], v[128:131], v[194:197], 0
	v_mfma_f32_16x16x32_bf16 v[104:107], v[152:155], v[194:197], 0
	v_mfma_f32_16x16x32_bf16 v[92:95], v[128:131], v[202:205], 0
	v_mfma_f32_16x16x32_bf16 v[88:91], v[152:155], v[202:205], 0
	v_mfma_f32_16x16x32_bf16 v[76:79], v[128:131], v[222:225], 0
	v_mfma_f32_16x16x32_bf16 v[72:75], v[152:155], v[222:225], 0
	v_mfma_f32_16x16x32_bf16 v[124:127], v[132:135], v[190:193], v[124:127]
	v_mfma_f32_16x16x32_bf16 v[120:123], v[156:159], v[190:193], v[120:123]
	v_mfma_f32_16x16x32_bf16 v[108:111], v[132:135], v[198:201], v[108:111]
	v_mfma_f32_16x16x32_bf16 v[104:107], v[156:159], v[198:201], v[104:107]
	v_mfma_f32_16x16x32_bf16 v[92:95], v[132:135], v[206:209], v[92:95]
	v_mfma_f32_16x16x32_bf16 v[88:91], v[156:159], v[206:209], v[88:91]
	v_mfma_f32_16x16x32_bf16 v[76:79], v[132:135], v[226:229], v[76:79]
	v_mfma_f32_16x16x32_bf16 v[72:75], v[156:159], v[226:229], v[72:75]
	v_mfma_f32_16x16x32_bf16 v[116:119], v[160:163], v[186:189], 0
	v_mfma_f32_16x16x32_bf16 v[112:115], v[168:171], v[186:189], 0
	v_mfma_f32_16x16x32_bf16 v[100:103], v[160:163], v[194:197], 0
	v_mfma_f32_16x16x32_bf16 v[96:99], v[168:171], v[194:197], 0
	v_mfma_f32_16x16x32_bf16 v[84:87], v[160:163], v[202:205], 0
	v_mfma_f32_16x16x32_bf16 v[80:83], v[168:171], v[202:205], 0
	v_mfma_f32_16x16x32_bf16 v[68:71], v[160:163], v[222:225], 0
	v_mfma_f32_16x16x32_bf16 v[64:67], v[168:171], v[222:225], 0
	v_mfma_f32_16x16x32_bf16 v[116:119], v[164:167], v[190:193], v[116:119]
	v_mfma_f32_16x16x32_bf16 v[112:115], v[182:185], v[190:193], v[112:115]
	v_mfma_f32_16x16x32_bf16 v[100:103], v[164:167], v[198:201], v[100:103]
	v_mfma_f32_16x16x32_bf16 v[96:99], v[182:185], v[198:201], v[96:99]
	v_mfma_f32_16x16x32_bf16 v[84:87], v[164:167], v[206:209], v[84:87]
	v_mfma_f32_16x16x32_bf16 v[80:83], v[182:185], v[206:209], v[80:83]
	v_mfma_f32_16x16x32_bf16 v[68:71], v[164:167], v[226:229], v[68:71]
	v_mfma_f32_16x16x32_bf16 v[64:67], v[182:185], v[226:229], v[64:67]
	s_barrier
	s_add_i32 s75, s75, s95
	v_lshl_add_u64 v[230:231], s[36:37], 0, v[138:139]
	s_mov_b32 m0, s75
	ds_read_b128 v[186:189], v220 offset:16384
	ds_read_b128 v[190:193], v220 offset:17408
	ds_read_b128 v[194:197], v220 offset:18432
	ds_read_b128 v[198:201], v220 offset:19456
	ds_read_b128 v[202:205], v220 offset:20480
	ds_read_b128 v[206:209], v220 offset:21504
	ds_read_b128 v[222:225], v220 offset:22528
	ds_read_b128 v[226:229], v220 offset:23552
	global_load_lds_dwordx4 v[230:231], off
	s_add_i32 m0, s75, 0x2000
	s_add_u32 s90, s36, 0x40000
	v_lshl_add_u64 v[232:233], s[36:37], 0, v[142:143]
	s_addc_u32 s91, s37, 0
	s_add_i32 s75, s89, s95
	global_load_lds_dwordx4 v[232:233], off
	v_lshl_add_u64 v[234:235], s[90:91], 0, v[138:139]
	s_mov_b32 m0, s75
	v_lshl_add_u64 v[236:237], s[52:53], 0, v[140:141]
	global_load_lds_dwordx4 v[234:235], off
	v_lshl_add_u64 v[234:235], s[90:91], 0, v[142:143]
	s_add_i32 m0, s75, 0x2000
	s_nop 0
	global_load_lds_dwordx4 v[234:235], off
	v_lshl_add_u64 v[234:235], s[52:53], 0, v[136:137]
	s_mov_b32 m0, s56
	s_nop 0
	global_load_lds_dwordx4 v[234:235], off
	s_mov_b32 m0, s57
	s_nop 0
	global_load_lds_dwordx4 v[236:237], off
	s_waitcnt vmcnt(8)
	s_waitcnt lgkmcnt(0)
	s_barrier
; #define PG8_STAGE(bufoff, gbase, voff) do { _Pragma("unroll") for (int _i = 0; _i < 2; ++_i) \
;         __builtin_amdgcn_global_load_lds((const GAS unsigned*)((const GAS char*)(gbase) + (voff)[_i]), (LAS unsigned*)(lds + (bufoff) + ldsw + _i * 8192), 16, 0, 0); } while (0)
; #define PG8_LDA(dst, b, h) do { _Pragma("unroll") for (int m = 0; m < 4; ++m) _Pragma("unroll") for (int k = 0; k < 2; ++k) dst[m][k] = *(const LAS bf16x8*)(lds + PG8_SA(b, h) + aoff + m * 2048 + k * 1024); } while (0)
; #define PG8_LDB(dst, b, h) do { _Pragma("unroll") for (int n = 0; n < 2; ++n) _Pragma("unroll") for (int k = 0; k < 2; ++k) dst[n][k] = *(const LAS bf16x8*)(lds + PG8_SB(b, h) + boff + n * 2048 + k * 1024); } while (0)
; #define PG8_MMA(ai, bj, At, Bt) do { __builtin_amdgcn_s_setprio(1); _Pragma("unroll") for (int m = 0; m < 4; ++m) _Pragma("unroll") for (int n = 0; n < 2; ++n) _Pragma("unroll") for (int k = 0; k < 2; ++k) \
;         acc[ai][bj][m][n] = __builtin_amdgcn_mfma_f32_16x16x32_bf16(Bt[n][k], At[m][k], acc[ai][bj][m][n], 0, 0, 0); __builtin_amdgcn_s_setprio(0); } while (0)
; #define PG8_WAIT_V(n) asm volatile("s_waitcnt vmcnt(" #n ")" ::: "memory")
; #define PG8_WAIT_L(n) asm volatile("s_waitcnt lgkmcnt(" #n ")" ::: "memory")
; #define PG8_BAR __builtin_amdgcn_s_barrier()
; #define PG8_SCHED __builtin_amdgcn_sched_barrier(0)
;     ...
;             PG8_WAIT_V(8); PG8_WAIT_L(0); PG8_BAR; PG8_MMA(1, 0, At, B0); PG8_MMA(1, 1, At, B1); PG8_BAR; PG8_SCHED;
;             PG8_LDB(B0, 1, 0); PG8_LDB(B1, 1, 1); PG8_SCHED; PG8_LDA(At, 1, 0); PG8_STAGE(PG8_SA(0, 1), a2 + hstep, voffA);
;             PG8_WAIT_V(8); PG8_WAIT_L(0); PG8_BAR; PG8_MMA(0, 0, At, B0); PG8_MMA(0, 1, At, B1); PG8_BAR; PG8_SCHED;
	s_waitcnt lgkmcnt(0)
	v_mfma_f32_16x16x32_bf16 v[60:63], v[128:131], v[186:189], 0
	v_mfma_f32_16x16x32_bf16 v[56:59], v[152:155], v[186:189], 0
	v_mfma_f32_16x16x32_bf16 v[44:47], v[128:131], v[194:197], 0
	v_mfma_f32_16x16x32_bf16 v[40:43], v[152:155], v[194:197], 0
	v_mfma_f32_16x16x32_bf16 v[28:31], v[128:131], v[202:205], 0
	v_mfma_f32_16x16x32_bf16 v[24:27], v[152:155], v[202:205], 0
	v_mfma_f32_16x16x32_bf16 v[12:15], v[128:131], v[222:225], 0
	v_mfma_f32_16x16x32_bf16 v[8:11], v[152:155], v[222:225], 0
	v_mfma_f32_16x16x32_bf16 v[60:63], v[132:135], v[190:193], v[60:63]
	v_mfma_f32_16x16x32_bf16 v[56:59], v[156:159], v[190:193], v[56:59]
	v_mfma_f32_16x16x32_bf16 v[44:47], v[132:135], v[198:201], v[44:47]
	v_mfma_f32_16x16x32_bf16 v[40:43], v[156:159], v[198:201], v[40:43]
	v_mfma_f32_16x16x32_bf16 v[28:31], v[132:135], v[206:209], v[28:31]
	v_mfma_f32_16x16x32_bf16 v[24:27], v[156:159], v[206:209], v[24:27]
	v_mfma_f32_16x16x32_bf16 v[12:15], v[132:135], v[226:229], v[12:15]
	v_mfma_f32_16x16x32_bf16 v[8:11], v[156:159], v[226:229], v[8:11]
	v_mfma_f32_16x16x32_bf16 v[52:55], v[160:163], v[186:189], 0
	v_mfma_f32_16x16x32_bf16 v[48:51], v[168:171], v[186:189], 0
	v_mfma_f32_16x16x32_bf16 v[36:39], v[160:163], v[194:197], 0
	v_mfma_f32_16x16x32_bf16 v[32:35], v[168:171], v[194:197], 0
	v_mfma_f32_16x16x32_bf16 v[20:23], v[160:163], v[202:205], 0
	v_mfma_f32_16x16x32_bf16 v[16:19], v[168:171], v[202:205], 0
	v_mfma_f32_16x16x32_bf16 v[4:7], v[160:163], v[222:225], 0
	v_mfma_f32_16x16x32_bf16 v[0:3], v[168:171], v[222:225], 0
	v_mfma_f32_16x16x32_bf16 v[52:55], v[164:167], v[190:193], v[52:55]
	v_mfma_f32_16x16x32_bf16 v[48:51], v[182:185], v[190:193], v[48:51]
	v_mfma_f32_16x16x32_bf16 v[36:39], v[164:167], v[198:201], v[36:39]
	v_mfma_f32_16x16x32_bf16 v[32:35], v[182:185], v[198:201], v[32:35]
	v_mfma_f32_16x16x32_bf16 v[20:23], v[164:167], v[206:209], v[20:23]
	v_mfma_f32_16x16x32_bf16 v[16:19], v[182:185], v[206:209], v[16:19]
	v_mfma_f32_16x16x32_bf16 v[4:7], v[164:167], v[226:229], v[4:7]
	v_mfma_f32_16x16x32_bf16 v[0:3], v[182:185], v[226:229], v[0:3]
	s_barrier
	s_add_i32 s75, 0, 0x18000
	s_add_i32 s89, 0, 0x1c000
	v_add_u32_e32 v156, s75, v218
	v_add_u32_e32 v172, s89, v218
	ds_read_b128 v[128:131], v156
	ds_read_b128 v[132:135], v156 offset:1024
	ds_read_b128 v[152:155], v156 offset:2048
	ds_read_b128 v[156:159], v156 offset:3072
	ds_read_b128 v[160:163], v172
	ds_read_b128 v[164:167], v172 offset:1024
	ds_read_b128 v[168:171], v172 offset:2048
	ds_read_b128 v[182:185], v172 offset:3072
	s_add_u32 s52, s52, 0x40000
	s_addc_u32 s53, s53, 0
	s_mov_b32 m0, s69
	v_lshl_add_u64 v[238:239], s[52:53], 0, v[136:137]
	ds_read_b128 v[186:189], v220 offset:32768
	ds_read_b128 v[190:193], v220 offset:33792
	ds_read_b128 v[194:197], v220 offset:34816
	ds_read_b128 v[198:201], v220 offset:35840
	ds_read_b128 v[202:205], v220 offset:36864
	ds_read_b128 v[206:209], v220 offset:37888
	ds_read_b128 v[222:225], v220 offset:38912
	ds_read_b128 v[226:229], v220 offset:39936
	global_load_lds_dwordx4 v[238:239], off
	v_lshl_add_u64 v[238:239], s[52:53], 0, v[140:141]
	s_mov_b32 m0, s66
	s_nop 0
	global_load_lds_dwordx4 v[238:239], off
	s_waitcnt vmcnt(8)
	s_waitcnt lgkmcnt(0)
	s_barrier
	s_waitcnt lgkmcnt(0)
	v_mfma_f32_16x16x32_bf16 v[124:127], v[128:131], v[186:189], v[124:127]
	v_mfma_f32_16x16x32_bf16 v[120:123], v[152:155], v[186:189], v[120:123]
	v_mfma_f32_16x16x32_bf16 v[108:111], v[128:131], v[194:197], v[108:111]
	v_mfma_f32_16x16x32_bf16 v[104:107], v[152:155], v[194:197], v[104:107]
	v_mfma_f32_16x16x32_bf16 v[92:95], v[128:131], v[202:205], v[92:95]
	v_mfma_f32_16x16x32_bf16 v[88:91], v[152:155], v[202:205], v[88:91]
	v_mfma_f32_16x16x32_bf16 v[76:79], v[128:131], v[222:225], v[76:79]
	v_mfma_f32_16x16x32_bf16 v[72:75], v[152:155], v[222:225], v[72:75]
	v_mfma_f32_16x16x32_bf16 v[124:127], v[132:135], v[190:193], v[124:127]
	v_mfma_f32_16x16x32_bf16 v[120:123], v[156:159], v[190:193], v[120:123]
	v_mfma_f32_16x16x32_bf16 v[108:111], v[132:135], v[198:201], v[108:111]
	v_mfma_f32_16x16x32_bf16 v[104:107], v[156:159], v[198:201], v[104:107]
	v_mfma_f32_16x16x32_bf16 v[92:95], v[132:135], v[206:209], v[92:95]
	v_mfma_f32_16x16x32_bf16 v[88:91], v[156:159], v[206:209], v[88:91]
	v_mfma_f32_16x16x32_bf16 v[76:79], v[132:135], v[226:229], v[76:79]
	v_mfma_f32_16x16x32_bf16 v[72:75], v[156:159], v[226:229], v[72:75]
	v_mfma_f32_16x16x32_bf16 v[116:119], v[160:163], v[186:189], v[116:119]
	v_mfma_f32_16x16x32_bf16 v[112:115], v[168:171], v[186:189], v[112:115]
	v_mfma_f32_16x16x32_bf16 v[100:103], v[160:163], v[194:197], v[100:103]
	v_mfma_f32_16x16x32_bf16 v[96:99], v[168:171], v[194:197], v[96:99]
	v_mfma_f32_16x16x32_bf16 v[84:87], v[160:163], v[202:205], v[84:87]
	v_mfma_f32_16x16x32_bf16 v[80:83], v[168:171], v[202:205], v[80:83]
	v_mfma_f32_16x16x32_bf16 v[68:71], v[160:163], v[222:225], v[68:71]
	v_mfma_f32_16x16x32_bf16 v[64:67], v[168:171], v[222:225], v[64:67]
	v_mfma_f32_16x16x32_bf16 v[116:119], v[164:167], v[190:193], v[116:119]
	v_mfma_f32_16x16x32_bf16 v[112:115], v[182:185], v[190:193], v[112:115]
	v_mfma_f32_16x16x32_bf16 v[100:103], v[164:167], v[198:201], v[100:103]
	v_mfma_f32_16x16x32_bf16 v[96:99], v[182:185], v[198:201], v[96:99]
	v_mfma_f32_16x16x32_bf16 v[84:87], v[164:167], v[206:209], v[84:87]
	v_mfma_f32_16x16x32_bf16 v[80:83], v[182:185], v[206:209], v[80:83]
	v_mfma_f32_16x16x32_bf16 v[68:71], v[164:167], v[226:229], v[68:71]
	v_mfma_f32_16x16x32_bf16 v[64:67], v[182:185], v[226:229], v[64:67]
	s_barrier
; #define GAS __attribute__((address_space(1)))
; #define PG8_STAGE(bufoff, gbase, voff) do { _Pragma("unroll") for (int _i = 0; _i < 2; ++_i) \
;         __builtin_amdgcn_global_load_lds((const GAS unsigned*)((const GAS char*)(gbase) + (voff)[_i]), (LAS unsigned*)(lds + (bufoff) + ldsw + _i * 8192), 16, 0, 0); } while (0)
; #define PG8_LDA(dst, b, h) do { _Pragma("unroll") for (int m = 0; m < 4; ++m) _Pragma("unroll") for (int k = 0; k < 2; ++k) dst[m][k] = *(const LAS bf16x8*)(lds + PG8_SA(b, h) + aoff + m * 2048 + k * 1024); } while (0)
; #define PG8_LDB(dst, b, h) do { _Pragma("unroll") for (int n = 0; n < 2; ++n) _Pragma("unroll") for (int k = 0; k < 2; ++k) dst[n][k] = *(const LAS bf16x8*)(lds + PG8_SB(b, h) + boff + n * 2048 + k * 1024); } while (0)
; #define PG8_MMA(ai, bj, At, Bt) do { __builtin_amdgcn_s_setprio(1); _Pragma("unroll") for (int m = 0; m < 4; ++m) _Pragma("unroll") for (int n = 0; n < 2; ++n) _Pragma("unroll") for (int k = 0; k < 2; ++k) \
;         acc[ai][bj][m][n] = __builtin_amdgcn_mfma_f32_16x16x32_bf16(Bt[n][k], At[m][k], acc[ai][bj][m][n], 0, 0, 0); __builtin_amdgcn_s_setprio(0); } while (0)
; #define PG8_WAIT_V(n) asm volatile("s_waitcnt vmcnt(" #n ")" ::: "memory")
; #define PG8_WAIT_L(n) asm volatile("s_waitcnt lgkmcnt(" #n ")" ::: "memory")
; #define PG8_BAR __builtin_amdgcn_s_barrier()
; #define PG8_SCHED __builtin_amdgcn_sched_barrier(0)
;     ...
;         for (int t = 0; t < nt; t += 2) {
;             const bool last = (t == nt - 2);
;             const GAS char* a1 = cA + (size_t)(t + 1) * kstep;
;             const GAS char* a2 = last ? nA : cA + (size_t)(t + 2) * kstep; const GAS char* b2 = last ? nB : cB + (size_t)(t + 2) * kstep;
;             const GAS char* a3 = a2 + kstep; const GAS char* b3 = b2 + kstep;
;             PG8_LDB(B0, 0, 0); PG8_LDB(B1, 0, 1); PG8_SCHED; PG8_LDA(At, 0, 0); PG8_STAGE(PG8_SA(1, 1), a1 + hstep, voffA);
;             PG8_WAIT_V(8); PG8_WAIT_L(0); PG8_BAR; PG8_MMA(0, 0, At, B0); PG8_MMA(0, 1, At, B1); PG8_BAR; PG8_SCHED;
;     ...
;             PG8_LDA(At, 1, 1); PG8_STAGE(PG8_SB(1, 0), b3, voffB); PG8_STAGE(PG8_SB(1, 1), b3 + hstep, voffB); PG8_STAGE(PG8_SA(1, 0), a3, voffA);
;             PG8_WAIT_V(8); PG8_WAIT_L(0); PG8_BAR; PG8_MMA(1, 0, At, B0); PG8_MMA(1, 1, At, B1); PG8_BAR; PG8_SCHED;
	s_add_i32 s52, s75, s95
	v_lshl_add_u64 v[230:231], v[230:231], 0, s[82:83]
	s_mov_b32 m0, s52
	ds_read_b128 v[186:189], v220 offset:49152
	ds_read_b128 v[190:193], v220 offset:50176
	ds_read_b128 v[194:197], v220 offset:51200
	ds_read_b128 v[198:201], v220 offset:52224
	ds_read_b128 v[202:205], v220 offset:53248
	ds_read_b128 v[206:209], v220 offset:54272
	ds_read_b128 v[222:225], v220 offset:55296
	ds_read_b128 v[226:229], v220 offset:56320
	global_load_lds_dwordx4 v[230:231], off
	s_add_i32 m0, s52, 0x2000
	s_add_u32 s36, s36, 0x40080
	v_lshl_add_u64 v[230:231], v[232:233], 0, s[82:83]
	s_addc_u32 s37, s37, 0
	s_add_i32 s52, s89, s95
	global_load_lds_dwordx4 v[230:231], off
	v_lshl_add_u64 v[230:231], s[36:37], 0, v[138:139]
	s_mov_b32 m0, s52
	s_nop 0
	global_load_lds_dwordx4 v[230:231], off
	v_lshl_add_u64 v[230:231], s[36:37], 0, v[142:143]
	s_add_i32 m0, s52, 0x2000
	s_nop 0
	global_load_lds_dwordx4 v[230:231], off
	v_lshl_add_u64 v[230:231], v[234:235], 0, s[82:83]
	s_mov_b32 m0, s67
	s_nop 0
	global_load_lds_dwordx4 v[230:231], off
	v_lshl_add_u64 v[230:231], v[236:237], 0, s[82:83]
	s_mov_b32 m0, s12
	s_nop 0
	global_load_lds_dwordx4 v[230:231], off
	s_waitcnt vmcnt(8)
	s_waitcnt lgkmcnt(0)
	s_barrier
	s_waitcnt lgkmcnt(0)
	v_mfma_f32_16x16x32_bf16 v[60:63], v[128:131], v[186:189], v[60:63]
	v_mfma_f32_16x16x32_bf16 v[56:59], v[152:155], v[186:189], v[56:59]
	v_mfma_f32_16x16x32_bf16 v[44:47], v[128:131], v[194:197], v[44:47]
	v_mfma_f32_16x16x32_bf16 v[40:43], v[152:155], v[194:197], v[40:43]
	v_mfma_f32_16x16x32_bf16 v[28:31], v[128:131], v[202:205], v[28:31]
	v_mfma_f32_16x16x32_bf16 v[24:27], v[152:155], v[202:205], v[24:27]
	v_mfma_f32_16x16x32_bf16 v[12:15], v[128:131], v[222:225], v[12:15]
	v_mfma_f32_16x16x32_bf16 v[8:11], v[152:155], v[222:225], v[8:11]
	v_mfma_f32_16x16x32_bf16 v[60:63], v[132:135], v[190:193], v[60:63]
	v_mfma_f32_16x16x32_bf16 v[56:59], v[156:159], v[190:193], v[56:59]
	v_mfma_f32_16x16x32_bf16 v[44:47], v[132:135], v[198:201], v[44:47]
	v_mfma_f32_16x16x32_bf16 v[40:43], v[156:159], v[198:201], v[40:43]
	v_mfma_f32_16x16x32_bf16 v[28:31], v[132:135], v[206:209], v[28:31]
	v_mfma_f32_16x16x32_bf16 v[24:27], v[156:159], v[206:209], v[24:27]
	v_mfma_f32_16x16x32_bf16 v[12:15], v[132:135], v[226:229], v[12:15]
	v_mfma_f32_16x16x32_bf16 v[8:11], v[156:159], v[226:229], v[8:11]
	v_mfma_f32_16x16x32_bf16 v[52:55], v[160:163], v[186:189], v[52:55]
	v_mfma_f32_16x16x32_bf16 v[48:51], v[168:171], v[186:189], v[48:51]
	v_mfma_f32_16x16x32_bf16 v[36:39], v[160:163], v[194:197], v[36:39]
	v_mfma_f32_16x16x32_bf16 v[32:35], v[168:171], v[194:197], v[32:35]
	v_mfma_f32_16x16x32_bf16 v[20:23], v[160:163], v[202:205], v[20:23]
	v_mfma_f32_16x16x32_bf16 v[16:19], v[168:171], v[202:205], v[16:19]
	v_mfma_f32_16x16x32_bf16 v[4:7], v[160:163], v[222:225], v[4:7]
	v_mfma_f32_16x16x32_bf16 v[0:3], v[168:171], v[222:225], v[0:3]
	v_mfma_f32_16x16x32_bf16 v[52:55], v[164:167], v[190:193], v[52:55]
	v_mfma_f32_16x16x32_bf16 v[48:51], v[182:185], v[190:193], v[48:51]
	v_mfma_f32_16x16x32_bf16 v[36:39], v[164:167], v[198:201], v[36:39]
	v_mfma_f32_16x16x32_bf16 v[32:35], v[182:185], v[198:201], v[32:35]
	v_mfma_f32_16x16x32_bf16 v[20:23], v[164:167], v[206:209], v[20:23]
	v_mfma_f32_16x16x32_bf16 v[16:19], v[182:185], v[206:209], v[16:19]
	v_mfma_f32_16x16x32_bf16 v[4:7], v[164:167], v[226:229], v[4:7]
	v_mfma_f32_16x16x32_bf16 v[0:3], v[182:185], v[226:229], v[0:3]
	s_barrier
	s_add_i32 s65, s65, 2
	s_add_u32 s63, s63, 0x100
	s_addc_u32 s64, s64, 0
	s_add_u32 s34, s34, 0x100
	s_addc_u32 s35, s35, 0
.LBB0_190:
	s_add_u32 s36, s34, 0xfffc0080
	s_addc_u32 s37, s35, -1
	s_add_i32 s75, 0, 0x10000
	s_cmp_eq_u32 s65, 12
	s_cselect_b32 s53, s17, s37
	s_cselect_b32 s52, s20, s36
	s_cselect_b32 s37, s25, s64
	s_cselect_b32 s36, s62, s63
	s_add_i32 s89, 0, 0x14000
	v_add_u32_e32 v156, s75, v218
	v_add_u32_e32 v172, s89, v218
	ds_read_b128 v[128:131], v156
	ds_read_b128 v[132:135], v156 offset:1024
	ds_read_b128 v[152:155], v156 offset:2048
	ds_read_b128 v[156:159], v156 offset:3072
	ds_read_b128 v[160:163], v172
	ds_read_b128 v[164:167], v172 offset:1024
	ds_read_b128 v[168:171], v172 offset:2048
	ds_read_b128 v[182:185], v172 offset:3072
	v_lshl_add_u64 v[230:231], s[34:35], 0, v[150:151]
	s_add_i32 m0, s56, 0xc000
	ds_read_b128 v[186:189], v220
	ds_read_b128 v[190:193], v220 offset:1024
	ds_read_b128 v[194:197], v220 offset:2048
	ds_read_b128 v[198:201], v220 offset:3072
	ds_read_b128 v[202:205], v220 offset:4096
	ds_read_b128 v[206:209], v220 offset:5120
	ds_read_b128 v[222:225], v220 offset:6144
	ds_read_b128 v[226:229], v220 offset:7168
	global_load_lds_dwordx4 v[230:231], off
	v_lshl_add_u64 v[230:231], s[34:35], 0, v[148:149]
	s_add_i32 m0, s56, 0xe000
	s_nop 0
	global_load_lds_dwordx4 v[230:231], off
	s_waitcnt vmcnt(8)
	s_waitcnt lgkmcnt(0)
	s_barrier
; #define PG8_STAGE(bufoff, gbase, voff) do { _Pragma("unroll") for (int _i = 0; _i < 2; ++_i) \
;         __builtin_amdgcn_global_load_lds((const GAS unsigned*)((const GAS char*)(gbase) + (voff)[_i]), (LAS unsigned*)(lds + (bufoff) + ldsw + _i * 8192), 16, 0, 0); } while (0)
; #define PG8_LDA(dst, b, h) do { _Pragma("unroll") for (int m = 0; m < 4; ++m) _Pragma("unroll") for (int k = 0; k < 2; ++k) dst[m][k] = *(const LAS bf16x8*)(lds + PG8_SA(b, h) + aoff + m * 2048 + k * 1024); } while (0)
; #define PG8_MMA(ai, bj, At, Bt) do { __builtin_amdgcn_s_setprio(1); _Pragma("unroll") for (int m = 0; m < 4; ++m) _Pragma("unroll") for (int n = 0; n < 2; ++n) _Pragma("unroll") for (int k = 0; k < 2; ++k) \
;         acc[ai][bj][m][n] = __builtin_amdgcn_mfma_f32_16x16x32_bf16(Bt[n][k], At[m][k], acc[ai][bj][m][n], 0, 0, 0); __builtin_amdgcn_s_setprio(0); } while (0)
; #define PG8_WAIT_V(n) asm volatile("s_waitcnt vmcnt(" #n ")" ::: "memory")
; #define PG8_WAIT_L(n) asm volatile("s_waitcnt lgkmcnt(" #n ")" ::: "memory")
; #define PG8_BAR __builtin_amdgcn_s_barrier()
; #define PG8_SCHED __builtin_amdgcn_sched_barrier(0)
;     ...
;             PG8_WAIT_V(8); PG8_WAIT_L(0); PG8_BAR; PG8_MMA(0, 0, At, B0); PG8_MMA(0, 1, At, B1); PG8_BAR; PG8_SCHED;
;             PG8_LDA(At, 0, 1); PG8_STAGE(PG8_SB(0, 0), b2, voffB); PG8_STAGE(PG8_SB(0, 1), b2 + hstep, voffB); PG8_STAGE(PG8_SA(0, 0), a2, voffA);
;             PG8_WAIT_V(8); PG8_WAIT_L(0); PG8_BAR; PG8_MMA(1, 0, At, B0); PG8_MMA(1, 1, At, B1); PG8_BAR; PG8_SCHED;
	s_waitcnt lgkmcnt(0)
	v_mfma_f32_16x16x32_bf16 v[124:127], v[128:131], v[186:189], v[124:127]
	v_mfma_f32_16x16x32_bf16 v[120:123], v[152:155], v[186:189], v[120:123]
	v_mfma_f32_16x16x32_bf16 v[108:111], v[128:131], v[194:197], v[108:111]
	v_mfma_f32_16x16x32_bf16 v[104:107], v[152:155], v[194:197], v[104:107]
	v_mfma_f32_16x16x32_bf16 v[92:95], v[128:131], v[202:205], v[92:95]
	v_mfma_f32_16x16x32_bf16 v[88:91], v[152:155], v[202:205], v[88:91]
	v_mfma_f32_16x16x32_bf16 v[76:79], v[128:131], v[222:225], v[76:79]
	v_mfma_f32_16x16x32_bf16 v[72:75], v[152:155], v[222:225], v[72:75]
	v_mfma_f32_16x16x32_bf16 v[124:127], v[132:135], v[190:193], v[124:127]
	v_mfma_f32_16x16x32_bf16 v[120:123], v[156:159], v[190:193], v[120:123]
	v_mfma_f32_16x16x32_bf16 v[108:111], v[132:135], v[198:201], v[108:111]
	v_mfma_f32_16x16x32_bf16 v[104:107], v[156:159], v[198:201], v[104:107]
	v_mfma_f32_16x16x32_bf16 v[92:95], v[132:135], v[206:209], v[92:95]
	v_mfma_f32_16x16x32_bf16 v[88:91], v[156:159], v[206:209], v[88:91]
	v_mfma_f32_16x16x32_bf16 v[76:79], v[132:135], v[226:229], v[76:79]
	v_mfma_f32_16x16x32_bf16 v[72:75], v[156:159], v[226:229], v[72:75]
	v_mfma_f32_16x16x32_bf16 v[116:119], v[160:163], v[186:189], v[116:119]
	v_mfma_f32_16x16x32_bf16 v[112:115], v[168:171], v[186:189], v[112:115]
	v_mfma_f32_16x16x32_bf16 v[100:103], v[160:163], v[194:197], v[100:103]
	v_mfma_f32_16x16x32_bf16 v[96:99], v[168:171], v[194:197], v[96:99]
	v_mfma_f32_16x16x32_bf16 v[84:87], v[160:163], v[202:205], v[84:87]
	v_mfma_f32_16x16x32_bf16 v[80:83], v[168:171], v[202:205], v[80:83]
	v_mfma_f32_16x16x32_bf16 v[68:71], v[160:163], v[222:225], v[68:71]
	v_mfma_f32_16x16x32_bf16 v[64:67], v[168:171], v[222:225], v[64:67]
	v_mfma_f32_16x16x32_bf16 v[116:119], v[164:167], v[190:193], v[116:119]
	v_mfma_f32_16x16x32_bf16 v[112:115], v[182:185], v[190:193], v[112:115]
	v_mfma_f32_16x16x32_bf16 v[100:103], v[164:167], v[198:201], v[100:103]
	v_mfma_f32_16x16x32_bf16 v[96:99], v[182:185], v[198:201], v[96:99]
	v_mfma_f32_16x16x32_bf16 v[84:87], v[164:167], v[206:209], v[84:87]
	v_mfma_f32_16x16x32_bf16 v[80:83], v[182:185], v[206:209], v[80:83]
	v_mfma_f32_16x16x32_bf16 v[68:71], v[164:167], v[226:229], v[68:71]
	v_mfma_f32_16x16x32_bf16 v[64:67], v[182:185], v[226:229], v[64:67]
	s_barrier
	s_add_i32 s75, s75, s95
	v_lshl_add_u64 v[230:231], s[36:37], 0, v[138:139]
	s_mov_b32 m0, s75
	ds_read_b128 v[186:189], v220 offset:16384
	ds_read_b128 v[190:193], v220 offset:17408
	ds_read_b128 v[194:197], v220 offset:18432
	ds_read_b128 v[198:201], v220 offset:19456
	ds_read_b128 v[202:205], v220 offset:20480
	ds_read_b128 v[206:209], v220 offset:21504
	ds_read_b128 v[222:225], v220 offset:22528
	ds_read_b128 v[226:229], v220 offset:23552
	global_load_lds_dwordx4 v[230:231], off
	s_add_i32 m0, s75, 0x2000
	s_add_u32 s90, s36, 0x40000
	v_lshl_add_u64 v[232:233], s[36:37], 0, v[142:143]
	s_addc_u32 s91, s37, 0
	s_add_i32 s75, s89, s95
	global_load_lds_dwordx4 v[232:233], off
	v_lshl_add_u64 v[234:235], s[90:91], 0, v[138:139]
	s_mov_b32 m0, s75
	v_lshl_add_u64 v[236:237], s[52:53], 0, v[140:141]
	global_load_lds_dwordx4 v[234:235], off
	v_lshl_add_u64 v[234:235], s[90:91], 0, v[142:143]
	s_add_i32 m0, s75, 0x2000
	s_nop 0
	global_load_lds_dwordx4 v[234:235], off
	v_lshl_add_u64 v[234:235], s[52:53], 0, v[136:137]
	s_mov_b32 m0, s56
	s_nop 0
	global_load_lds_dwordx4 v[234:235], off
	s_mov_b32 m0, s57
	s_nop 0
	global_load_lds_dwordx4 v[236:237], off
	s_waitcnt vmcnt(8)
	s_waitcnt lgkmcnt(0)
	s_barrier
	s_waitcnt lgkmcnt(0)
	v_mfma_f32_16x16x32_bf16 v[60:63], v[128:131], v[186:189], v[60:63]
	v_mfma_f32_16x16x32_bf16 v[56:59], v[152:155], v[186:189], v[56:59]
	v_mfma_f32_16x16x32_bf16 v[44:47], v[128:131], v[194:197], v[44:47]
	v_mfma_f32_16x16x32_bf16 v[40:43], v[152:155], v[194:197], v[40:43]
	v_mfma_f32_16x16x32_bf16 v[28:31], v[128:131], v[202:205], v[28:31]
	v_mfma_f32_16x16x32_bf16 v[24:27], v[152:155], v[202:205], v[24:27]
	v_mfma_f32_16x16x32_bf16 v[12:15], v[128:131], v[222:225], v[12:15]
	v_mfma_f32_16x16x32_bf16 v[8:11], v[152:155], v[222:225], v[8:11]
	v_mfma_f32_16x16x32_bf16 v[60:63], v[132:135], v[190:193], v[60:63]
	v_mfma_f32_16x16x32_bf16 v[56:59], v[156:159], v[190:193], v[56:59]
	v_mfma_f32_16x16x32_bf16 v[44:47], v[132:135], v[198:201], v[44:47]
	v_mfma_f32_16x16x32_bf16 v[40:43], v[156:159], v[198:201], v[40:43]
	v_mfma_f32_16x16x32_bf16 v[28:31], v[132:135], v[206:209], v[28:31]
	v_mfma_f32_16x16x32_bf16 v[24:27], v[156:159], v[206:209], v[24:27]
	v_mfma_f32_16x16x32_bf16 v[12:15], v[132:135], v[226:229], v[12:15]
	v_mfma_f32_16x16x32_bf16 v[8:11], v[156:159], v[226:229], v[8:11]
	v_mfma_f32_16x16x32_bf16 v[52:55], v[160:163], v[186:189], v[52:55]
	v_mfma_f32_16x16x32_bf16 v[48:51], v[168:171], v[186:189], v[48:51]
	v_mfma_f32_16x16x32_bf16 v[36:39], v[160:163], v[194:197], v[36:39]
	v_mfma_f32_16x16x32_bf16 v[32:35], v[168:171], v[194:197], v[32:35]
	v_mfma_f32_16x16x32_bf16 v[20:23], v[160:163], v[202:205], v[20:23]
	v_mfma_f32_16x16x32_bf16 v[16:19], v[168:171], v[202:205], v[16:19]
	v_mfma_f32_16x16x32_bf16 v[4:7], v[160:163], v[222:225], v[4:7]
	v_mfma_f32_16x16x32_bf16 v[0:3], v[168:171], v[222:225], v[0:3]
	v_mfma_f32_16x16x32_bf16 v[52:55], v[164:167], v[190:193], v[52:55]
	v_mfma_f32_16x16x32_bf16 v[48:51], v[182:185], v[190:193], v[48:51]
	v_mfma_f32_16x16x32_bf16 v[36:39], v[164:167], v[198:201], v[36:39]
	v_mfma_f32_16x16x32_bf16 v[32:35], v[182:185], v[198:201], v[32:35]
	v_mfma_f32_16x16x32_bf16 v[20:23], v[164:167], v[206:209], v[20:23]
	v_mfma_f32_16x16x32_bf16 v[16:19], v[182:185], v[206:209], v[16:19]
	v_mfma_f32_16x16x32_bf16 v[4:7], v[164:167], v[226:229], v[4:7]
	v_mfma_f32_16x16x32_bf16 v[0:3], v[182:185], v[226:229], v[0:3]
	s_barrier
; #define PG8_STAGE(bufoff, gbase, voff) do { _Pragma("unroll") for (int _i = 0; _i < 2; ++_i) \
;         __builtin_amdgcn_global_load_lds((const GAS unsigned*)((const GAS char*)(gbase) + (voff)[_i]), (LAS unsigned*)(lds + (bufoff) + ldsw + _i * 8192), 16, 0, 0); } while (0)
; #define PG8_LDA(dst, b, h) do { _Pragma("unroll") for (int m = 0; m < 4; ++m) _Pragma("unroll") for (int k = 0; k < 2; ++k) dst[m][k] = *(const LAS bf16x8*)(lds + PG8_SA(b, h) + aoff + m * 2048 + k * 1024); } while (0)
; #define PG8_LDB(dst, b, h) do { _Pragma("unroll") for (int n = 0; n < 2; ++n) _Pragma("unroll") for (int k = 0; k < 2; ++k) dst[n][k] = *(const LAS bf16x8*)(lds + PG8_SB(b, h) + boff + n * 2048 + k * 1024); } while (0)
; #define PG8_MMA(ai, bj, At, Bt) do { __builtin_amdgcn_s_setprio(1); _Pragma("unroll") for (int m = 0; m < 4; ++m) _Pragma("unroll") for (int n = 0; n < 2; ++n) _Pragma("unroll") for (int k = 0; k < 2; ++k) \
;         acc[ai][bj][m][n] = __builtin_amdgcn_mfma_f32_16x16x32_bf16(Bt[n][k], At[m][k], acc[ai][bj][m][n], 0, 0, 0); __builtin_amdgcn_s_setprio(0); } while (0)
; #define PG8_WAIT_V(n) asm volatile("s_waitcnt vmcnt(" #n ")" ::: "memory")
; #define PG8_WAIT_L(n) asm volatile("s_waitcnt lgkmcnt(" #n ")" ::: "memory")
; #define PG8_BAR __builtin_amdgcn_s_barrier()
; #define PG8_SCHED __builtin_amdgcn_sched_barrier(0)
;     ...
;             PG8_LDB(B0, 1, 0); PG8_LDB(B1, 1, 1); PG8_SCHED; PG8_LDA(At, 1, 0); PG8_STAGE(PG8_SA(0, 1), a2 + hstep, voffA);
;             PG8_WAIT_V(8); PG8_WAIT_L(0); PG8_BAR; PG8_MMA(0, 0, At, B0); PG8_MMA(0, 1, At, B1); PG8_BAR; PG8_SCHED;
	s_add_i32 s75, 0, 0x18000
	s_add_i32 s89, 0, 0x1c000
	v_add_u32_e32 v156, s75, v218
	v_add_u32_e32 v172, s89, v218
	ds_read_b128 v[128:131], v156
	ds_read_b128 v[132:135], v156 offset:1024
	ds_read_b128 v[152:155], v156 offset:2048
	ds_read_b128 v[156:159], v156 offset:3072
	ds_read_b128 v[160:163], v172
	ds_read_b128 v[164:167], v172 offset:1024
	ds_read_b128 v[168:171], v172 offset:2048
	ds_read_b128 v[182:185], v172 offset:3072
	s_add_u32 s52, s52, 0x40000
	s_addc_u32 s53, s53, 0
	s_mov_b32 m0, s69
	v_lshl_add_u64 v[238:239], s[52:53], 0, v[136:137]
	ds_read_b128 v[186:189], v220 offset:32768
	ds_read_b128 v[190:193], v220 offset:33792
	ds_read_b128 v[194:197], v220 offset:34816
	ds_read_b128 v[198:201], v220 offset:35840
	ds_read_b128 v[202:205], v220 offset:36864
	ds_read_b128 v[206:209], v220 offset:37888
	ds_read_b128 v[222:225], v220 offset:38912
	ds_read_b128 v[226:229], v220 offset:39936
	global_load_lds_dwordx4 v[238:239], off
	v_lshl_add_u64 v[238:239], s[52:53], 0, v[140:141]
	s_mov_b32 m0, s66
	s_nop 0
	global_load_lds_dwordx4 v[238:239], off
	s_waitcnt vmcnt(8)
	s_waitcnt lgkmcnt(0)
	s_barrier
	s_waitcnt lgkmcnt(0)
	v_mfma_f32_16x16x32_bf16 v[124:127], v[128:131], v[186:189], v[124:127]
	v_mfma_f32_16x16x32_bf16 v[120:123], v[152:155], v[186:189], v[120:123]
	v_mfma_f32_16x16x32_bf16 v[108:111], v[128:131], v[194:197], v[108:111]
	v_mfma_f32_16x16x32_bf16 v[104:107], v[152:155], v[194:197], v[104:107]
	v_mfma_f32_16x16x32_bf16 v[92:95], v[128:131], v[202:205], v[92:95]
	v_mfma_f32_16x16x32_bf16 v[88:91], v[152:155], v[202:205], v[88:91]
	v_mfma_f32_16x16x32_bf16 v[76:79], v[128:131], v[222:225], v[76:79]
	v_mfma_f32_16x16x32_bf16 v[72:75], v[152:155], v[222:225], v[72:75]
	v_mfma_f32_16x16x32_bf16 v[124:127], v[132:135], v[190:193], v[124:127]
	v_mfma_f32_16x16x32_bf16 v[120:123], v[156:159], v[190:193], v[120:123]
	v_mfma_f32_16x16x32_bf16 v[108:111], v[132:135], v[198:201], v[108:111]
	v_mfma_f32_16x16x32_bf16 v[104:107], v[156:159], v[198:201], v[104:107]
	v_mfma_f32_16x16x32_bf16 v[92:95], v[132:135], v[206:209], v[92:95]
	v_mfma_f32_16x16x32_bf16 v[88:91], v[156:159], v[206:209], v[88:91]
	v_mfma_f32_16x16x32_bf16 v[76:79], v[132:135], v[226:229], v[76:79]
	v_mfma_f32_16x16x32_bf16 v[72:75], v[156:159], v[226:229], v[72:75]
	v_mfma_f32_16x16x32_bf16 v[116:119], v[160:163], v[186:189], v[116:119]
	v_mfma_f32_16x16x32_bf16 v[112:115], v[168:171], v[186:189], v[112:115]
	v_mfma_f32_16x16x32_bf16 v[100:103], v[160:163], v[194:197], v[100:103]
	v_mfma_f32_16x16x32_bf16 v[96:99], v[168:171], v[194:197], v[96:99]
	v_mfma_f32_16x16x32_bf16 v[84:87], v[160:163], v[202:205], v[84:87]
	v_mfma_f32_16x16x32_bf16 v[80:83], v[168:171], v[202:205], v[80:83]
	v_mfma_f32_16x16x32_bf16 v[68:71], v[160:163], v[222:225], v[68:71]
	v_mfma_f32_16x16x32_bf16 v[64:67], v[168:171], v[222:225], v[64:67]
	v_mfma_f32_16x16x32_bf16 v[116:119], v[164:167], v[190:193], v[116:119]
	v_mfma_f32_16x16x32_bf16 v[112:115], v[182:185], v[190:193], v[112:115]
	v_mfma_f32_16x16x32_bf16 v[100:103], v[164:167], v[198:201], v[100:103]
	v_mfma_f32_16x16x32_bf16 v[96:99], v[182:185], v[198:201], v[96:99]
	v_mfma_f32_16x16x32_bf16 v[84:87], v[164:167], v[206:209], v[84:87]
	v_mfma_f32_16x16x32_bf16 v[80:83], v[182:185], v[206:209], v[80:83]
	v_mfma_f32_16x16x32_bf16 v[68:71], v[164:167], v[226:229], v[68:71]
	v_mfma_f32_16x16x32_bf16 v[64:67], v[182:185], v[226:229], v[64:67]
	s_barrier
; #define PG8_STAGE(bufoff, gbase, voff) do { _Pragma("unroll") for (int _i = 0; _i < 2; ++_i) \
;         __builtin_amdgcn_global_load_lds((const GAS unsigned*)((const GAS char*)(gbase) + (voff)[_i]), (LAS unsigned*)(lds + (bufoff) + ldsw + _i * 8192), 16, 0, 0); } while (0)
; #define PG8_LDA(dst, b, h) do { _Pragma("unroll") for (int m = 0; m < 4; ++m) _Pragma("unroll") for (int k = 0; k < 2; ++k) dst[m][k] = *(const LAS bf16x8*)(lds + PG8_SA(b, h) + aoff + m * 2048 + k * 1024); } while (0)
; #define PG8_MMA(ai, bj, At, Bt) do { __builtin_amdgcn_s_setprio(1); _Pragma("unroll") for (int m = 0; m < 4; ++m) _Pragma("unroll") for (int n = 0; n < 2; ++n) _Pragma("unroll") for (int k = 0; k < 2; ++k) \
;         acc[ai][bj][m][n] = __builtin_amdgcn_mfma_f32_16x16x32_bf16(Bt[n][k], At[m][k], acc[ai][bj][m][n], 0, 0, 0); __builtin_amdgcn_s_setprio(0); } while (0)
; #define PG8_WAIT_V(n) asm volatile("s_waitcnt vmcnt(" #n ")" ::: "memory")
; #define PG8_WAIT_L(n) asm volatile("s_waitcnt lgkmcnt(" #n ")" ::: "memory")
; #define PG8_BAR __builtin_amdgcn_s_barrier()
; #define PG8_SCHED __builtin_amdgcn_sched_barrier(0)
;     ...
;             PG8_LDA(At, 1, 1); PG8_STAGE(PG8_SB(1, 0), b3, voffB); PG8_STAGE(PG8_SB(1, 1), b3 + hstep, voffB); PG8_STAGE(PG8_SA(1, 0), a3, voffA);
;             PG8_WAIT_V(8); PG8_WAIT_L(0); PG8_BAR; PG8_MMA(1, 0, At, B0); PG8_MMA(1, 1, At, B1); PG8_BAR; PG8_SCHED;
;         }
;         if (wr == 0) PG8_BAR;
	s_add_i32 s52, s75, s95
	v_lshl_add_u64 v[230:231], v[230:231], 0, s[82:83]
	s_mov_b32 m0, s52
	ds_read_b128 v[186:189], v220 offset:49152
	ds_read_b128 v[190:193], v220 offset:50176
	ds_read_b128 v[194:197], v220 offset:51200
	ds_read_b128 v[198:201], v220 offset:52224
	ds_read_b128 v[202:205], v220 offset:53248
	ds_read_b128 v[206:209], v220 offset:54272
	ds_read_b128 v[222:225], v220 offset:55296
	ds_read_b128 v[226:229], v220 offset:56320
	global_load_lds_dwordx4 v[230:231], off
	s_add_i32 m0, s52, 0x2000
	s_add_u32 s36, s36, 0x40080
	v_lshl_add_u64 v[230:231], v[232:233], 0, s[82:83]
	s_addc_u32 s37, s37, 0
	s_add_i32 s52, s89, s95
	global_load_lds_dwordx4 v[230:231], off
	v_lshl_add_u64 v[230:231], s[36:37], 0, v[138:139]
	s_mov_b32 m0, s52
	s_nop 0
	global_load_lds_dwordx4 v[230:231], off
	v_lshl_add_u64 v[230:231], s[36:37], 0, v[142:143]
	s_add_i32 m0, s52, 0x2000
	s_nop 0
	global_load_lds_dwordx4 v[230:231], off
	v_lshl_add_u64 v[230:231], v[234:235], 0, s[82:83]
	s_mov_b32 m0, s67
	s_nop 0
	global_load_lds_dwordx4 v[230:231], off
	v_lshl_add_u64 v[230:231], v[236:237], 0, s[82:83]
	s_mov_b32 m0, s12
	s_nop 0
	global_load_lds_dwordx4 v[230:231], off
	s_waitcnt vmcnt(8)
	s_waitcnt lgkmcnt(0)
	s_barrier
	s_waitcnt lgkmcnt(0)
	v_mfma_f32_16x16x32_bf16 v[60:63], v[128:131], v[186:189], v[60:63]
	v_mfma_f32_16x16x32_bf16 v[56:59], v[152:155], v[186:189], v[56:59]
	v_mfma_f32_16x16x32_bf16 v[44:47], v[128:131], v[194:197], v[44:47]
	v_mfma_f32_16x16x32_bf16 v[40:43], v[152:155], v[194:197], v[40:43]
	v_mfma_f32_16x16x32_bf16 v[28:31], v[128:131], v[202:205], v[28:31]
	v_mfma_f32_16x16x32_bf16 v[24:27], v[152:155], v[202:205], v[24:27]
	v_mfma_f32_16x16x32_bf16 v[12:15], v[128:131], v[222:225], v[12:15]
	v_mfma_f32_16x16x32_bf16 v[8:11], v[152:155], v[222:225], v[8:11]
	v_mfma_f32_16x16x32_bf16 v[60:63], v[132:135], v[190:193], v[60:63]
	v_mfma_f32_16x16x32_bf16 v[56:59], v[156:159], v[190:193], v[56:59]
	v_mfma_f32_16x16x32_bf16 v[44:47], v[132:135], v[198:201], v[44:47]
	v_mfma_f32_16x16x32_bf16 v[40:43], v[156:159], v[198:201], v[40:43]
	v_mfma_f32_16x16x32_bf16 v[28:31], v[132:135], v[206:209], v[28:31]
	v_mfma_f32_16x16x32_bf16 v[24:27], v[156:159], v[206:209], v[24:27]
	v_mfma_f32_16x16x32_bf16 v[12:15], v[132:135], v[226:229], v[12:15]
	v_mfma_f32_16x16x32_bf16 v[8:11], v[156:159], v[226:229], v[8:11]
	v_mfma_f32_16x16x32_bf16 v[52:55], v[160:163], v[186:189], v[52:55]
	v_mfma_f32_16x16x32_bf16 v[48:51], v[168:171], v[186:189], v[48:51]
	v_mfma_f32_16x16x32_bf16 v[36:39], v[160:163], v[194:197], v[36:39]
	v_mfma_f32_16x16x32_bf16 v[32:35], v[168:171], v[194:197], v[32:35]
	v_mfma_f32_16x16x32_bf16 v[20:23], v[160:163], v[202:205], v[20:23]
	v_mfma_f32_16x16x32_bf16 v[16:19], v[168:171], v[202:205], v[16:19]
	v_mfma_f32_16x16x32_bf16 v[4:7], v[160:163], v[222:225], v[4:7]
	v_mfma_f32_16x16x32_bf16 v[0:3], v[168:171], v[222:225], v[0:3]
	v_mfma_f32_16x16x32_bf16 v[52:55], v[164:167], v[190:193], v[52:55]
	v_mfma_f32_16x16x32_bf16 v[48:51], v[182:185], v[190:193], v[48:51]
	v_mfma_f32_16x16x32_bf16 v[36:39], v[164:167], v[198:201], v[36:39]
	v_mfma_f32_16x16x32_bf16 v[32:35], v[182:185], v[198:201], v[32:35]
	v_mfma_f32_16x16x32_bf16 v[20:23], v[164:167], v[206:209], v[20:23]
	v_mfma_f32_16x16x32_bf16 v[16:19], v[182:185], v[206:209], v[16:19]
	v_mfma_f32_16x16x32_bf16 v[4:7], v[164:167], v[226:229], v[4:7]
	v_mfma_f32_16x16x32_bf16 v[0:3], v[182:185], v[226:229], v[0:3]
	s_barrier
	s_add_i32 s65, s65, 2
	s_add_u32 s63, s63, 0x100
	s_addc_u32 s64, s64, 0
	s_add_u32 s34, s34, 0x100
	s_addc_u32 s35, s35, 0
	s_cmp_gt_u32 s65, 13
	s_cbranch_scc0 .LBB0_190
	v_readlane_b32 s34, v243, 62
	v_readlane_b32 s35, v243, 63
	s_and_b64 vcc, exec, s[34:35]
	s_cbranch_vccz .LBB0_193
	s_barrier

; #define GAS __attribute__((address_space(1)))
; __device__ __forceinline__ int lane_id() { unsigned z = 0u; asm volatile("" : "+v"(z)); return (int)__builtin_amdgcn_mbcnt_hi(~0u, __builtin_amdgcn_mbcnt_lo(~0u, z)); }
; __device__ __forceinline__ void xcd_barrier(const XcdBarrier& b, int wave) {
;     asm volatile("s_waitcnt vmcnt(0)" ::: "memory");
;     __syncthreads();
;     if (wave == 0 && lane_id() == 0) {
;         GAS unsigned* bar = b.bar;
;         __builtin_amdgcn_s_waitcnt(0);
;         unsigned nloc = b.st[0], nx = b.st[1];
;         if (nloc == 0u) { xcd_barrier_complete(bar, b.x, nloc, nx); b.st[0] = nloc; b.st[1] = nx; }
.LBB0_504:
	s_setprio 0
	v_readlane_b32 s8, v240, 7
	s_add_i32 s12, s8, 3
	s_cmp_ge_i32 s12, s65
	s_cbranch_scc1 .LBB0_551
	s_waitcnt vmcnt(0)
	s_and_b64 vcc, exec, s[54:55]
	s_waitcnt vmcnt(0)
	s_barrier
	s_cbranch_vccnz .LBB0_550
	v_mov_b32_e32 v0, v173
	s_nop 0
	v_mbcnt_lo_u32_b32 v0, -1, v0
	v_mbcnt_hi_u32_b32 v0, -1, v0
	v_cmp_eq_u32_e32 vcc, 0, v0
	s_and_saveexec_b64 s[8:9], vcc
	s_cbranch_execz .LBB0_549
	v_readlane_b32 s13, v243, 2
	s_waitcnt vmcnt(0) expcnt(0) lgkmcnt(0)
	s_nop 0
	v_mov_b32_e32 v0, s13
	ds_read_b32 v2, v0
	ds_read_b32 v1, v0 offset:4
	s_waitcnt lgkmcnt(1)
	v_cmp_ne_u32_e32 vcc, 0, v2
	s_cbranch_vccnz .LBB0_520
	v_readlane_b32 s16, v243, 0
	v_readlane_b32 s17, v243, 1
	s_load_dwordx2 s[14:15], s[16:17], 0x4
	s_waitcnt lgkmcnt(0)
	s_mul_i32 s13, s14, s2
	s_mul_i32 s13, s13, s15
	s_mov_b32 s14, 1
	s_branch .LBB0_510

; #define SEAM(k) do { if (IN(k) && IN((k) + 1)) xcd_barrier(bar, F.wave); } while (0)
; __global__ void __launch_bounds__(512, 2) mega_fwd(Params p) {
;     ...
;             } SEAM(pb + 1);
;         if (IN(pb + 2)) { phase_mixers(F, l, l); } SEAM(pb + 2);
.LBB0_551:
	s_setprio 0
	v_readlane_b32 s8, v240, 5
	v_readlane_b32 s9, v240, 6
	s_xor_b64 s[8:9], s[8:9], -1
	v_writelane_b32 v240, s8, 19
	s_nop 1
	v_writelane_b32 v240, s9, 20
	s_nop 0
	v_readlane_b32 s8, v240, 10
	v_readlane_b32 s9, v240, 11
	s_xor_b64 s[34:35], s[8:9], -1
	s_cmp_le_i32 s64, s12
	s_cselect_b64 s[8:9], -1, 0
	s_cmp_lt_i32 s12, s65
	s_cselect_b64 s[12:13], -1, 0
	s_and_b64 s[12:13], s[8:9], s[12:13]
	s_mov_b64 s[8:9], -1
	s_and_b64 vcc, exec, s[12:13]
	s_cbranch_vccnz .LBB0_553
	v_readlane_b32 s8, v240, 7
	s_add_i32 s14, s8, 4
	s_mov_b64 s[8:9], 0
